# m3 gate preamble: DPP scans instead of ds_bpermute hops (m1 unchanged)
# baseline (speedup 1.0000x reference)
.LBB0_449:
	s_ashr_i32 s2, s39, 10
	s_and_b32 s41, s39, 0x7f
	s_ashr_i32 s3, s2, 31
	v_mov_b32_e32 v23, v194
	s_lshl_b64 s[34:35], s[2:3], 13
	s_lshl_b32 s2, s41, 6
	s_bfe_u32 s42, s39, 0x30007
	v_readfirstlane_b32 s40, v23
	s_or_b32 s34, s34, s2
	s_cmp_gt_u32 s40, 63
	v_and_b32_e32 v22, 63, v23
	s_cbranch_scc1 .LBB0_451
	v_or_b32_e32 v0, s34, v22
	v_mov_b32_e32 v1, s35
	v_lshlrev_b64 v[0:1], 6, v[0:1]
	v_lshl_add_u64 v[0:1], s[30:31], 0, v[0:1]
	s_lshl_b32 s86, s42, 2
	v_lshl_add_u64 v[0:1], v[0:1], 0, s[86:87]
	v_mov_b32_e32 v3, s86
	global_load_dword v2, v[0:1], off offset:32
	global_load_dword v4, v3, s[26:27]
	s_nop 0
	global_load_dword v0, v[0:1], off
	s_nop 0
	global_load_dword v1, v3, s[28:29]
	s_lshl_b32 s98, s39, 4
	s_add_u32 s98, s0, s98
	s_addc_u32 s99, s1, 0
	v_mov_b32_e32 v41, 0x18100000
	global_load_dword v42, v41, s[98:99] offset:8
	s_mov_b32 s2, 0x3f317218
	s_waitcnt vmcnt(2)
	v_add_f32_e32 v2, v2, v4
	s_waitcnt vmcnt(0)
	v_add_f32_e32 v1, v0, v1
	v_min_f32_e32 v0, 0, v2
	v_mul_f32_e64 v2, |v2|, s79
	v_exp_f32_e32 v4, v2
	s_nop 0
	v_add_f32_e32 v5, 1.0, v4
	v_add_f32_e32 v2, -1.0, v5
	v_sub_f32_e32 v3, v2, v5
	v_add_f32_e32 v3, 1.0, v3
	v_sub_f32_e32 v2, v4, v2
	v_add_f32_e32 v6, v2, v3
	v_frexp_mant_f32_e32 v2, v5
	v_cmp_gt_f32_e32 vcc, s85, v2
	v_cvt_f64_f32_e32 v[2:3], v5
	v_frexp_exp_i32_f64_e32 v2, v[2:3]
	v_subbrev_co_u32_e32 v2, vcc, 0, v2, vcc
	v_sub_u32_e32 v3, 0, v2
	v_ldexp_f32 v5, v5, v3
	v_ldexp_f32 v3, v6, v3
	v_add_f32_e32 v6, -1.0, v5
	v_add_f32_e32 v7, 1.0, v6
	v_sub_f32_e32 v7, v5, v7
	v_add_f32_e32 v7, v3, v7
	v_add_f32_e32 v8, v6, v7
	v_sub_f32_e32 v6, v8, v6
	v_sub_f32_e32 v6, v7, v6
	v_add_f32_e32 v7, 1.0, v5
	v_add_f32_e32 v9, -1.0, v7
	v_sub_f32_e32 v5, v5, v9
	v_add_f32_e32 v3, v3, v5
	v_add_f32_e32 v5, v7, v3
	v_sub_f32_e32 v7, v5, v7
	v_sub_f32_e32 v3, v3, v7
	v_rcp_f32_e32 v7, v5
	v_cvt_f32_i32_e32 v2, v2
	v_mul_f32_e32 v9, v8, v7
	v_mul_f32_e32 v10, v5, v9
	v_fma_f32 v11, v9, v5, -v10
	v_fmac_f32_e32 v11, v9, v3
	v_add_f32_e32 v12, v10, v11
	v_sub_f32_e32 v13, v8, v12
	v_sub_f32_e32 v8, v8, v13
	v_sub_f32_e32 v10, v12, v10
	v_sub_f32_e32 v8, v8, v12
	v_add_f32_e32 v6, v6, v8
	v_sub_f32_e32 v8, v10, v11
	v_add_f32_e32 v6, v8, v6
	v_add_f32_e32 v8, v13, v6
	v_mul_f32_e32 v10, v7, v8
	v_mul_f32_e32 v11, v5, v10
	v_fma_f32 v5, v10, v5, -v11
	v_fmac_f32_e32 v5, v10, v3
	v_sub_f32_e32 v3, v13, v8
	v_add_f32_e32 v3, v6, v3
	v_add_f32_e32 v6, v11, v5
	v_sub_f32_e32 v12, v8, v6
	v_sub_f32_e32 v8, v8, v12
	v_sub_f32_e32 v11, v6, v11
	v_sub_f32_e32 v6, v8, v6
	v_add_f32_e32 v3, v3, v6
	v_sub_f32_e32 v5, v11, v5
	v_add_f32_e32 v3, v5, v3
	v_add_f32_e32 v5, v9, v10
	v_add_f32_e32 v3, v12, v3
	v_sub_f32_e32 v6, v5, v9
	v_mul_f32_e32 v3, v7, v3
	v_sub_f32_e32 v6, v10, v6
	v_add_f32_e32 v3, v6, v3
	v_mul_f32_e32 v9, 0x3f317218, v2
	v_add_f32_e32 v6, v5, v3
	v_fma_f32 v10, v2, s2, -v9
	v_mul_f32_e32 v7, v6, v6
	v_fmac_f32_e32 v10, 0xb102e308, v2
	v_sub_f32_e32 v2, v6, v5
	v_fmamk_f32 v8, v7, 0x3e9b6dac, v200
	v_sub_f32_e32 v2, v3, v2
	v_add_f32_e32 v3, v9, v10
	v_fmaak_f32 v8, v7, v8, 0x3f2aaada
	v_sub_f32_e32 v5, v3, v9
	v_ldexp_f32 v9, v6, 1
	v_mul_f32_e32 v6, v6, v7
	v_mul_f32_e32 v6, v6, v8
	v_add_f32_e32 v7, v9, v6
	v_sub_f32_e32 v8, v7, v9
	v_ldexp_f32 v2, v2, 1
	v_sub_f32_e32 v6, v6, v8
	v_add_f32_e32 v2, v2, v6
	v_add_f32_e32 v6, v7, v2
	v_sub_f32_e32 v7, v6, v7
	v_sub_f32_e32 v2, v2, v7
	v_add_f32_e32 v7, v3, v6
	v_sub_f32_e32 v8, v7, v3
	v_sub_f32_e32 v9, v7, v8
	v_sub_f32_e32 v5, v10, v5
	v_sub_f32_e32 v3, v3, v9
	v_sub_f32_e32 v6, v6, v8
	v_add_f32_e32 v3, v6, v3
	v_add_f32_e32 v6, v5, v2
	v_sub_f32_e32 v8, v6, v5
	v_sub_f32_e32 v9, v6, v8
	v_sub_f32_e32 v5, v5, v9
	v_sub_f32_e32 v2, v2, v8
	v_add_f32_e32 v3, v6, v3
	v_add_f32_e32 v2, v2, v5
	v_add_f32_e32 v5, v7, v3
	v_sub_f32_e32 v6, v5, v7
	v_sub_f32_e32 v3, v3, v6
	v_add_f32_e32 v2, v2, v3
	s_mov_b32 s2, 0x7f800000
	v_add_f32_e32 v2, v5, v2
	v_cmp_neq_f32_e32 vcc, s2, v4
	s_mov_b32 s2, 0x33800000
	v_add_u32_e32 v3, -1, v201
	v_cndmask_b32_e32 v2, v202, v2, vcc
	v_cmp_ngt_f32_e32 vcc, -1.0, v4
	s_nop 1
	v_cndmask_b32_e32 v2, v203, v2, vcc
	v_cmp_neq_f32_e32 vcc, -1.0, v4
	s_nop 1
	v_cndmask_b32_e32 v2, v204, v2, vcc
	v_cmp_lt_f32_e64 vcc, |v4|, s2
	s_lshl_b32 s2, s39, 2
	s_ashr_i32 s3, s2, 31
	v_cndmask_b32_e32 v2, v2, v4, vcc
	v_sub_f32_e32 v0, v0, v2
	v_mov_b32_e32 v4, v0
	s_nop 1
	v_add_f32_dpp v4, v0, v4 row_shr:1 row_mask:0xf bank_mask:0xf
	v_add_f32_dpp v4, v0, v4 row_shr:2 row_mask:0xf bank_mask:0xf
	v_add_f32_dpp v4, v0, v4 row_shr:3 row_mask:0xf bank_mask:0xf
	s_nop 1
	v_add_f32_dpp v4, v4, v4 row_shr:4 row_mask:0xf bank_mask:0xe
	s_nop 1
	v_add_f32_dpp v4, v4, v4 row_shr:8 row_mask:0xf bank_mask:0xc
	s_nop 1
	v_add_f32_dpp v4, v4, v4 row_bcast:15 row_mask:0xa bank_mask:0xf
	s_nop 1
	v_add_f32_dpp v4, v4, v4 row_bcast:31 row_mask:0xc bank_mask:0xf
	v_mov_b32_e32 v0, v4
	v_sub_f32_e32 v1, v1, v0
	v_mov_b32_e32 v3, v1
	s_nop 1
	v_max_f32_dpp v3, v1, v3 row_shr:1 row_mask:0xf bank_mask:0xf
	v_max_f32_dpp v3, v1, v3 row_shr:2 row_mask:0xf bank_mask:0xf
	v_max_f32_dpp v3, v1, v3 row_shr:3 row_mask:0xf bank_mask:0xf
	s_nop 1
	v_max_f32_dpp v3, v3, v3 row_shr:4 row_mask:0xf bank_mask:0xe
	s_nop 1
	v_max_f32_dpp v3, v3, v3 row_shr:8 row_mask:0xf bank_mask:0xc
	s_nop 1
	v_max_f32_dpp v3, v3, v3 row_bcast:15 row_mask:0xa bank_mask:0xf
	s_nop 1
	v_max_f32_dpp v3, v3, v3 row_bcast:31 row_mask:0xc bank_mask:0xf
	v_mov_b32_e32 v2, v3
	v_max_f32_e32 v2, v2, v2
	s_waitcnt vmcnt(0)
	v_mov_b32_e32 v3, v42
	v_max_f32_e32 v4, v3, v3
	v_max_f32_e32 v2, v4, v2
	v_lshl_add_u32 v4, v22, 2, 0
	v_add_u32_e32 v4, 0x19200, v4
	ds_write2st64_b32 v4, v1, v2 offset1:1
	v_sub_f32_e32 v1, v3, v2
	v_add_f32_e32 v0, v0, v2
	v_mul_f32_e32 v1, 0x3fb8aa3b, v1
	v_mul_f32_e32 v0, 0xbfb8aa3b, v0
	v_exp_f32_e32 v1, v1
	v_exp_f32_e32 v0, v0
	ds_write2st64_b32 v4, v1, v0 offset0:2 offset1:3
